# conversion seam allocation 0x2,2,5x2,6x2 (both seam-1 items moved to the idle waves of seam 0; seam 1 conversion-free) on v226
# baseline (speedup 1.0000x reference)
.Lmy_cv0_entry:
	s_mov_b64 exec, -1
	s_cmpk_lg_i32 s3, 0x100
	s_cbranch_scc1 .Lmy_cv0_done
	v_readfirstlane_b32 s44, v0
	s_nop 0
	s_lshr_b32 s44, s44, 6
	s_mul_i32 s7, s2, 7
	s_add_i32 s44, s44, s7
	s_add_i32 s44, s44, 12287
	s_cmp_gt_u32 s44, 0x5fff
	s_cbranch_scc1 .Lmy_cv0_done
	s_mov_b32 s6, s44
	v_and_b32_e32 v1, 63, v0
	v_readlane_b32 s10, v254, 2
	v_readlane_b32 s11, v254, 3
	s_sub_u32 s10, s10, 0xc8
	s_subb_u32 s11, s11, 0
	s_cmp_lt_u32 s6, 0x1600
	s_cbranch_scc1 .Lmy_cv0a_g1
	s_cmp_lt_u32 s6, 0x2c00
	s_cbranch_scc1 .Lmy_cv0a_u1
	s_cmp_lt_u32 s6, 0x3400
	s_cbranch_scc1 .Lmy_cv0a_wo
	s_cmp_lt_u32 s6, 0x4a00
	s_cbranch_scc1 .Lmy_cv0a_g2
	s_load_dwordx2 s[12:13], s[10:11], 0xa0
	s_sub_u32 s6, s6, 0x4a00
	s_movk_i32 s14, 0x80
	s_mov_b32 s20, 0x6a00000
	s_branch .Lmy_cv0a_gu

.Lmy_cv0a_gu:
	s_mul_i32 s15, s6, 0x1746
	s_lshr_b32 s15, s15, 20
	s_mul_i32 s42, s15, 0xb0
	s_sub_u32 s42, s6, s42
	s_lshl_b32 s43, s42, 5
	s_lshr_b32 s18, s43, 7
	s_lshl_b32 s18, s18, 8
	s_and_b32 s19, s43, 0x7f
	s_add_u32 s18, s18, s19
	s_add_u32 s18, s18, s14
	s_movk_i32 s19, 0x1600
	s_branch .Lmy_cv0a_go
.Lmy_cv0a_wo:
	s_load_dwordx2 s[12:13], s[10:11], 0x88
	s_sub_u32 s6, s6, 0x2c00
	s_lshr_b32 s15, s6, 6
	s_and_b32 s42, s6, 63
	s_lshl_b32 s43, s42, 5
	s_mov_b32 s18, s43
	s_movk_i32 s19, 0x800
	s_mov_b32 s20, 0x6200000
.Lmy_cv0a_go:
	s_add_u32 s20, s50, s20
	s_addc_u32 s21, s51, 0
	v_and_b32_e32 v2, 7, v1
	v_lshrrev_b32_e32 v3, 3, v1
	s_lshl_b32 s24, s15, 6
	v_lshl_add_u32 v4, v2, 3, s24
	v_mul_lo_u32 v4, v4, s19
	v_lshl_add_u32 v5, v3, 2, s43
	v_add_u32_e32 v4, v4, v5
	v_mov_b32_e32 v5, 0
	v_lshlrev_b64 v[4:5], 2, v[4:5]
	s_lshl_b32 s26, s19, 2
	s_mov_b32 s27, 0
	s_lshr_b32 s28, s18, 8
	s_and_b32 s29, s18, 0xff
	s_lshl_b32 s28, s28, 5
	s_add_u32 s28, s28, s15
	s_lshl_b32 s28, s28, 8
	s_add_u32 s28, s28, s29
	s_waitcnt lgkmcnt(0)
	v_lshl_add_u64 v[4:5], s[12:13], 0, v[4:5]
	global_load_dwordx4 v[8:11], v[4:5], off nt
	v_lshl_add_u64 v[4:5], v[4:5], 0, s[26:27]
	global_load_dwordx4 v[12:15], v[4:5], off nt
	v_lshl_add_u64 v[4:5], v[4:5], 0, s[26:27]
	global_load_dwordx4 v[16:19], v[4:5], off nt
	v_lshl_add_u64 v[4:5], v[4:5], 0, s[26:27]
	global_load_dwordx4 v[20:23], v[4:5], off nt
	v_lshl_add_u64 v[4:5], v[4:5], 0, s[26:27]
	global_load_dwordx4 v[24:27], v[4:5], off nt
	v_lshl_add_u64 v[4:5], v[4:5], 0, s[26:27]
	global_load_dwordx4 v[28:31], v[4:5], off nt
	v_lshl_add_u64 v[4:5], v[4:5], 0, s[26:27]
	global_load_dwordx4 v[32:35], v[4:5], off nt
	v_lshl_add_u64 v[4:5], v[4:5], 0, s[26:27]
	global_load_dwordx4 v[36:39], v[4:5], off nt
	v_lshl_add_u32 v6, v3, 2, s28
	v_lshlrev_b32_e32 v6, 7, v6
	v_lshl_add_u32 v6, v2, 4, v6
	v_mov_b32_e32 v7, 0
	v_lshl_add_u64 v[6:7], s[20:21], 0, v[6:7]
	s_add_i32 s6, s44, 1792
	s_cmp_gt_u32 s6, 0x5fff
	s_cbranch_scc1 .Lmy_cv0_one
	v_and_b32_e32 v1, 63, v0
	v_readlane_b32 s10, v254, 2
	v_readlane_b32 s11, v254, 3
	s_sub_u32 s10, s10, 0xc8
	s_subb_u32 s11, s11, 0
	s_cmp_lt_u32 s6, 0x1600
	s_cbranch_scc1 .Lmy_cv0b_g1
	s_cmp_lt_u32 s6, 0x2c00
	s_cbranch_scc1 .Lmy_cv0b_u1
	s_cmp_lt_u32 s6, 0x3400
	s_cbranch_scc1 .Lmy_cv0b_wo
	s_cmp_lt_u32 s6, 0x4a00
	s_cbranch_scc1 .Lmy_cv0b_g2
	s_load_dwordx2 s[12:13], s[10:11], 0xa0
	s_sub_u32 s6, s6, 0x4a00
	s_movk_i32 s14, 0x80
	s_mov_b32 s20, 0x6a00000
	s_branch .Lmy_cv0b_gu

.Lmy_cv0b_go:
	s_add_u32 s20, s50, s20
	s_addc_u32 s21, s51, 0
	v_and_b32_e32 v2, 7, v1
	v_lshrrev_b32_e32 v3, 3, v1
	s_lshl_b32 s24, s15, 6
	v_lshl_add_u32 v4, v2, 3, s24
	v_mul_lo_u32 v4, v4, s19
	v_lshl_add_u32 v5, v3, 2, s43
	v_add_u32_e32 v4, v4, v5
	v_mov_b32_e32 v5, 0
	v_lshlrev_b64 v[4:5], 2, v[4:5]
	s_lshl_b32 s26, s19, 2
	s_mov_b32 s27, 0
	s_lshr_b32 s28, s18, 8
	s_and_b32 s29, s18, 0xff
	s_lshl_b32 s28, s28, 5
	s_add_u32 s28, s28, s15
	s_lshl_b32 s28, s28, 8
	s_add_u32 s28, s28, s29
	s_waitcnt lgkmcnt(0)
	v_lshl_add_u64 v[4:5], s[12:13], 0, v[4:5]
	global_load_dwordx4 v[64:67], v[4:5], off nt
	v_lshl_add_u64 v[4:5], v[4:5], 0, s[26:27]
	global_load_dwordx4 v[68:71], v[4:5], off nt
	v_lshl_add_u64 v[4:5], v[4:5], 0, s[26:27]
	global_load_dwordx4 v[72:75], v[4:5], off nt
	v_lshl_add_u64 v[4:5], v[4:5], 0, s[26:27]
	global_load_dwordx4 v[76:79], v[4:5], off nt
	v_lshl_add_u64 v[4:5], v[4:5], 0, s[26:27]
	global_load_dwordx4 v[80:83], v[4:5], off nt
	v_lshl_add_u64 v[4:5], v[4:5], 0, s[26:27]
	global_load_dwordx4 v[84:87], v[4:5], off nt
	v_lshl_add_u64 v[4:5], v[4:5], 0, s[26:27]
	global_load_dwordx4 v[88:91], v[4:5], off nt
	v_lshl_add_u64 v[4:5], v[4:5], 0, s[26:27]
	global_load_dwordx4 v[92:95], v[4:5], off nt
	v_lshl_add_u32 v62, v3, 2, s28
	v_lshlrev_b32_e32 v62, 7, v62
	v_lshl_add_u32 v62, v2, 4, v62
	v_mov_b32_e32 v63, 0
	v_lshl_add_u64 v[62:63], s[20:21], 0, v[62:63]
	s_waitcnt vmcnt(8)
	v_cvt_pk_bf16_f32 v40, v8, v12
	v_cvt_pk_bf16_f32 v41, v16, v20
	v_cvt_pk_bf16_f32 v42, v24, v28
	v_cvt_pk_bf16_f32 v43, v32, v36
	global_store_dwordx4 v[6:7], v[40:43], off sc1
	v_cvt_pk_bf16_f32 v44, v9, v13
	v_cvt_pk_bf16_f32 v45, v17, v21
	v_cvt_pk_bf16_f32 v46, v25, v29
	v_cvt_pk_bf16_f32 v47, v33, v37
	global_store_dwordx4 v[6:7], v[44:47], off offset:128 sc1
	v_cvt_pk_bf16_f32 v48, v10, v14
	v_cvt_pk_bf16_f32 v49, v18, v22
	v_cvt_pk_bf16_f32 v50, v26, v30
	v_cvt_pk_bf16_f32 v51, v34, v38
	global_store_dwordx4 v[6:7], v[48:51], off offset:256 sc1
	v_cvt_pk_bf16_f32 v52, v11, v15
	v_cvt_pk_bf16_f32 v53, v19, v23
	v_cvt_pk_bf16_f32 v54, v27, v31
	v_cvt_pk_bf16_f32 v55, v35, v39
	global_store_dwordx4 v[6:7], v[52:55], off offset:384 sc1
	s_waitcnt vmcnt(4)
	v_cvt_pk_bf16_f32 v96, v64, v68
	v_cvt_pk_bf16_f32 v97, v72, v76
	v_cvt_pk_bf16_f32 v98, v80, v84
	v_cvt_pk_bf16_f32 v99, v88, v92
	global_store_dwordx4 v[62:63], v[96:99], off sc1
	v_cvt_pk_bf16_f32 v100, v65, v69
	v_cvt_pk_bf16_f32 v101, v73, v77
	v_cvt_pk_bf16_f32 v102, v81, v85
	v_cvt_pk_bf16_f32 v103, v89, v93
	global_store_dwordx4 v[62:63], v[100:103], off offset:128 sc1
	v_cvt_pk_bf16_f32 v104, v66, v70
	v_cvt_pk_bf16_f32 v105, v74, v78
	v_cvt_pk_bf16_f32 v106, v82, v86
	v_cvt_pk_bf16_f32 v107, v90, v94
	global_store_dwordx4 v[62:63], v[104:107], off offset:256 sc1
	v_cvt_pk_bf16_f32 v108, v67, v71
	v_cvt_pk_bf16_f32 v109, v75, v79
	v_cvt_pk_bf16_f32 v110, v83, v87
	v_cvt_pk_bf16_f32 v111, v91, v95
	global_store_dwordx4 v[62:63], v[108:111], off offset:384 sc1
	s_branch .Lmy_cv0_fin
